# relu^2 GEMM epilogues (phases 4, 12): the 128 NaN-canonicalising v_max per tile removed (store-data hazard kept with s_nop 1)
# baseline (speedup 1.0000x reference)
; __device__ __forceinline__ unsigned cvt_pk_bf16(float lo, float hi) { unsigned r; asm volatile("v_cvt_pk_bf16_f32 %0, %1, %2" : "=v"(r) : "v"(lo), "v"(hi)); return r; }
;     __device__ __forceinline__ void operator()(const f32x4 (&acc)[2][2][4][2], const Unit& u, int wr, int wc, int fr, int fq) const {
;     ...
;             for (int m = 0; m < 4; ++m) { bf16_t* rowp = O + (size_t)(row0 + ai * HALF + m * 16) * ldc + col0;
; #pragma unroll
;                 for (int bj = 0; bj < 2; ++bj) { f32x4 v0 = acc[ai][bj][m][0], v1 = acc[ai][bj][m][1];
;                     if (ACT == 1) { v0 = __builtin_elementwise_max(v0, (f32x4){0.f, 0.f, 0.f, 0.f}); v1 = __builtin_elementwise_max(v1, (f32x4){0.f, 0.f, 0.f, 0.f}); v0 = v0 * v0; v1 = v1 * v1; }
;                     if (ACT == 2) { v0 = v0 * sv[bj][0]; v1 = v1 * sv[bj][1]; }
;                     u32x4 w; w.x = cvt_pk_bf16(v0[0], v0[1]); w.y = cvt_pk_bf16(v0[2], v0[3]); w.z = cvt_pk_bf16(v1[0], v1[1]); w.w = cvt_pk_bf16(v1[2], v1[3]);
;                     *(u32x4*)(rowp + bj * HALF) = w; } }
.LBB0_381:
	v_lshl_add_u32 v148, s68, 8, v1
	v_lshl_or_b32 v146, s15, 8, v153
	v_ashrrev_i32_e32 v149, 31, v148
	v_ashrrev_i32_e32 v147, 31, v146
	v_lshlrev_b64 v[150:151], 13, v[148:149]
	v_lshl_add_u64 v[158:159], s[20:21], 0, v[150:151]
	v_lshlrev_b64 v[150:151], 1, v[146:147]
	v_max_f32_e32 v127, 0, v127
	v_max_f32_e32 v126, 0, v126
	v_max_f32_e32 v129, 0, v129
	v_max_f32_e32 v128, 0, v128
	v_max_f32_e32 v123, 0, v123
	v_max_f32_e32 v122, 0, v122
	v_max_f32_e32 v125, 0, v125
	v_max_f32_e32 v124, 0, v124
	v_lshl_add_u64 v[146:147], v[158:159], 0, v[150:151]
	v_pk_mul_f32 v[128:129], v[128:129], v[128:129]
	v_pk_mul_f32 v[126:127], v[126:127], v[126:127]
	v_pk_mul_f32 v[158:159], v[124:125], v[124:125]
	v_pk_mul_f32 v[124:125], v[122:123], v[122:123]
	v_cvt_pk_bf16_f32 v122, v126, v127
	v_cvt_pk_bf16_f32 v123, v128, v129
	v_max_f32_e32 v119, 0, v119
	v_max_f32_e32 v118, 0, v118
	v_max_f32_e32 v115, 0, v115
	v_max_f32_e32 v114, 0, v114
	v_max_f32_e32 v117, 0, v117
	v_max_f32_e32 v116, 0, v116
	v_cvt_pk_bf16_f32 v124, v124, v125
	v_cvt_pk_bf16_f32 v125, v158, v159
	global_store_dwordx4 v[146:147], v[122:125], off
	s_nop 1
	v_max_f32_e32 v121, 0, v121
	v_max_f32_e32 v120, 0, v120
	v_pk_mul_f32 v[118:119], v[118:119], v[118:119]
	v_pk_mul_f32 v[122:123], v[116:117], v[116:117]
	v_pk_mul_f32 v[116:117], v[114:115], v[114:115]
	v_cvt_pk_bf16_f32 v114, v118, v119
	v_pk_mul_f32 v[120:121], v[120:121], v[120:121]
	v_cvt_pk_bf16_f32 v115, v120, v121
	v_cvt_pk_bf16_f32 v116, v116, v117
	v_cvt_pk_bf16_f32 v117, v122, v123
	global_store_dwordx4 v[146:147], v[114:117], off offset:256
	s_nop 1
	v_or_b32_e32 v114, 16, v148
	v_ashrrev_i32_e32 v115, 31, v114
	v_lshlrev_b64 v[114:115], 13, v[114:115]
	v_lshl_add_u64 v[114:115], s[20:21], 0, v[114:115]
	v_max_f32_e32 v111, 0, v111
	v_max_f32_e32 v110, 0, v110
	v_max_f32_e32 v113, 0, v113
	v_max_f32_e32 v112, 0, v112
	v_max_f32_e32 v107, 0, v107
	v_max_f32_e32 v106, 0, v106
	v_max_f32_e32 v109, 0, v109
	v_max_f32_e32 v108, 0, v108
	v_lshl_add_u64 v[114:115], v[114:115], 0, v[150:151]
	v_pk_mul_f32 v[112:113], v[112:113], v[112:113]
	v_pk_mul_f32 v[110:111], v[110:111], v[110:111]
	v_pk_mul_f32 v[116:117], v[108:109], v[108:109]
	v_pk_mul_f32 v[108:109], v[106:107], v[106:107]
	v_cvt_pk_bf16_f32 v106, v110, v111
	v_cvt_pk_bf16_f32 v107, v112, v113
	v_max_f32_e32 v103, 0, v103
	v_max_f32_e32 v102, 0, v102
	v_max_f32_e32 v99, 0, v99
	v_max_f32_e32 v98, 0, v98
	v_max_f32_e32 v101, 0, v101
	v_max_f32_e32 v100, 0, v100
	v_cvt_pk_bf16_f32 v108, v108, v109
	v_cvt_pk_bf16_f32 v109, v116, v117
	global_store_dwordx4 v[114:115], v[106:109], off
	s_nop 1
	v_max_f32_e32 v105, 0, v105
	v_max_f32_e32 v104, 0, v104
	v_pk_mul_f32 v[102:103], v[102:103], v[102:103]
	v_pk_mul_f32 v[106:107], v[100:101], v[100:101]
	v_pk_mul_f32 v[100:101], v[98:99], v[98:99]
	v_cvt_pk_bf16_f32 v98, v102, v103
	v_pk_mul_f32 v[104:105], v[104:105], v[104:105]
	v_cvt_pk_bf16_f32 v99, v104, v105
	v_cvt_pk_bf16_f32 v100, v100, v101
	v_cvt_pk_bf16_f32 v101, v106, v107
	global_store_dwordx4 v[114:115], v[98:101], off offset:256
	s_nop 1
	v_or_b32_e32 v98, 32, v148
	v_ashrrev_i32_e32 v99, 31, v98
	v_lshlrev_b64 v[98:99], 13, v[98:99]
	v_lshl_add_u64 v[98:99], s[20:21], 0, v[98:99]
	v_max_f32_e32 v95, 0, v95
	v_max_f32_e32 v94, 0, v94
	v_max_f32_e32 v97, 0, v97
	v_max_f32_e32 v96, 0, v96
	v_max_f32_e32 v91, 0, v91
	v_max_f32_e32 v90, 0, v90
	v_max_f32_e32 v93, 0, v93
	v_max_f32_e32 v92, 0, v92
	v_lshl_add_u64 v[98:99], v[98:99], 0, v[150:151]
	v_pk_mul_f32 v[96:97], v[96:97], v[96:97]
	v_pk_mul_f32 v[94:95], v[94:95], v[94:95]
	v_pk_mul_f32 v[100:101], v[92:93], v[92:93]
	v_pk_mul_f32 v[92:93], v[90:91], v[90:91]
	v_cvt_pk_bf16_f32 v90, v94, v95
	v_cvt_pk_bf16_f32 v91, v96, v97
	v_max_f32_e32 v87, 0, v87
	v_max_f32_e32 v86, 0, v86
	v_max_f32_e32 v83, 0, v83
	v_max_f32_e32 v82, 0, v82
	v_max_f32_e32 v85, 0, v85
	v_max_f32_e32 v84, 0, v84
	v_cvt_pk_bf16_f32 v92, v92, v93
	v_cvt_pk_bf16_f32 v93, v100, v101
	global_store_dwordx4 v[98:99], v[90:93], off
	s_nop 1
	v_max_f32_e32 v89, 0, v89
	v_max_f32_e32 v88, 0, v88
	v_pk_mul_f32 v[86:87], v[86:87], v[86:87]
	v_pk_mul_f32 v[90:91], v[84:85], v[84:85]
	v_pk_mul_f32 v[84:85], v[82:83], v[82:83]
	v_cvt_pk_bf16_f32 v82, v86, v87
	v_pk_mul_f32 v[88:89], v[88:89], v[88:89]
	v_cvt_pk_bf16_f32 v83, v88, v89
	v_cvt_pk_bf16_f32 v84, v84, v85
	v_cvt_pk_bf16_f32 v85, v90, v91
	global_store_dwordx4 v[98:99], v[82:85], off offset:256
	s_nop 1
	v_or_b32_e32 v82, 48, v148
	v_ashrrev_i32_e32 v83, 31, v82
	v_lshlrev_b64 v[82:83], 13, v[82:83]
	v_lshl_add_u64 v[82:83], s[20:21], 0, v[82:83]
	v_max_f32_e32 v79, 0, v79
	v_max_f32_e32 v78, 0, v78
	v_max_f32_e32 v81, 0, v81
	v_max_f32_e32 v80, 0, v80
	v_max_f32_e32 v75, 0, v75
	v_max_f32_e32 v74, 0, v74
	v_max_f32_e32 v77, 0, v77
	v_max_f32_e32 v76, 0, v76
	v_lshl_add_u64 v[82:83], v[82:83], 0, v[150:151]
	v_pk_mul_f32 v[80:81], v[80:81], v[80:81]
	v_pk_mul_f32 v[78:79], v[78:79], v[78:79]
	v_pk_mul_f32 v[84:85], v[76:77], v[76:77]
	v_pk_mul_f32 v[76:77], v[74:75], v[74:75]
	v_cvt_pk_bf16_f32 v74, v78, v79
	v_cvt_pk_bf16_f32 v75, v80, v81
	v_max_f32_e32 v67, 0, v67
	v_max_f32_e32 v66, 0, v66
	v_max_f32_e32 v69, 0, v69
	v_max_f32_e32 v68, 0, v68
	v_cvt_pk_bf16_f32 v76, v76, v77
	v_cvt_pk_bf16_f32 v77, v84, v85
	global_store_dwordx4 v[82:83], v[74:77], off
	s_nop 1
	v_max_f32_e32 v71, 0, v71
	v_max_f32_e32 v70, 0, v70
	v_max_f32_e32 v73, 0, v73
	v_max_f32_e32 v72, 0, v72
	v_pk_mul_f32 v[74:75], v[68:69], v[68:69]
	v_pk_mul_f32 v[68:69], v[66:67], v[66:67]
	v_max_f32_e32 v63, 0, v63
; __device__ __forceinline__ unsigned cvt_pk_bf16(float lo, float hi) { unsigned r; asm volatile("v_cvt_pk_bf16_f32 %0, %1, %2" : "=v"(r) : "v"(lo), "v"(hi)); return r; }
;     __device__ __forceinline__ void operator()(const f32x4 (&acc)[2][2][4][2], const Unit& u, int wr, int wc, int fr, int fq) const {
;     ...
;             for (int m = 0; m < 4; ++m) { bf16_t* rowp = O + (size_t)(row0 + ai * HALF + m * 16) * ldc + col0;
; #pragma unroll
;                 for (int bj = 0; bj < 2; ++bj) { f32x4 v0 = acc[ai][bj][m][0], v1 = acc[ai][bj][m][1];
;                     if (ACT == 1) { v0 = __builtin_elementwise_max(v0, (f32x4){0.f, 0.f, 0.f, 0.f}); v1 = __builtin_elementwise_max(v1, (f32x4){0.f, 0.f, 0.f, 0.f}); v0 = v0 * v0; v1 = v1 * v1; }
;                     if (ACT == 2) { v0 = v0 * sv[bj][0]; v1 = v1 * sv[bj][1]; }
;                     u32x4 w; w.x = cvt_pk_bf16(v0[0], v0[1]); w.y = cvt_pk_bf16(v0[2], v0[3]); w.z = cvt_pk_bf16(v1[0], v1[1]); w.w = cvt_pk_bf16(v1[2], v1[3]);
;                     *(u32x4*)(rowp + bj * HALF) = w; } }
	v_max_f32_e32 v62, 0, v62
	v_pk_mul_f32 v[72:73], v[72:73], v[72:73]
	v_pk_mul_f32 v[70:71], v[70:71], v[70:71]
	v_cvt_pk_bf16_f32 v66, v70, v71
	v_cvt_pk_bf16_f32 v67, v72, v73
	v_cvt_pk_bf16_f32 v68, v68, v69
	v_cvt_pk_bf16_f32 v69, v74, v75
	v_max_f32_e32 v59, 0, v59
	v_max_f32_e32 v58, 0, v58
	v_max_f32_e32 v61, 0, v61
	v_max_f32_e32 v60, 0, v60
	v_pk_mul_f32 v[62:63], v[62:63], v[62:63]
	global_store_dwordx4 v[82:83], v[66:69], off offset:256
	s_nop 1
	v_max_f32_e32 v65, 0, v65
	v_max_f32_e32 v64, 0, v64
	v_pk_mul_f32 v[68:69], v[60:61], v[60:61]
	v_pk_mul_f32 v[60:61], v[58:59], v[58:59]
	v_cvt_pk_bf16_f32 v58, v62, v63
	v_add_co_u32_e32 v62, vcc, s89, v146
	v_pk_mul_f32 v[64:65], v[64:65], v[64:65]
	v_addc_co_u32_e32 v63, vcc, 0, v147, vcc
	v_cvt_pk_bf16_f32 v59, v64, v65
	v_max_f32_e32 v51, 0, v51
	v_max_f32_e32 v50, 0, v50
	v_max_f32_e32 v53, 0, v53
	v_max_f32_e32 v52, 0, v52
	v_cvt_pk_bf16_f32 v60, v60, v61
	v_cvt_pk_bf16_f32 v61, v68, v69
	global_store_dwordx4 v[62:63], v[58:61], off
	s_nop 1
	v_max_f32_e32 v55, 0, v55
	v_max_f32_e32 v54, 0, v54
	v_max_f32_e32 v57, 0, v57
	v_max_f32_e32 v56, 0, v56
	v_pk_mul_f32 v[58:59], v[52:53], v[52:53]
	v_pk_mul_f32 v[52:53], v[50:51], v[50:51]
	v_max_f32_e32 v47, 0, v47
	v_max_f32_e32 v46, 0, v46
	v_lshl_add_u64 v[66:67], v[146:147], 0, s[38:39]
	v_pk_mul_f32 v[56:57], v[56:57], v[56:57]
	v_pk_mul_f32 v[54:55], v[54:55], v[54:55]
	v_cvt_pk_bf16_f32 v50, v54, v55
	v_cvt_pk_bf16_f32 v51, v56, v57
	v_cvt_pk_bf16_f32 v52, v52, v53
	v_cvt_pk_bf16_f32 v53, v58, v59
	v_max_f32_e32 v43, 0, v43
	v_max_f32_e32 v42, 0, v42
	v_max_f32_e32 v45, 0, v45
	v_max_f32_e32 v44, 0, v44
	v_pk_mul_f32 v[46:47], v[46:47], v[46:47]
	global_store_dwordx4 v[66:67], v[50:53], off offset:256
	s_nop 1
	v_max_f32_e32 v49, 0, v49
	v_max_f32_e32 v48, 0, v48
	v_pk_mul_f32 v[52:53], v[44:45], v[44:45]
	v_pk_mul_f32 v[44:45], v[42:43], v[42:43]
	v_cvt_pk_bf16_f32 v42, v46, v47
	v_add_co_u32_e32 v46, vcc, s91, v146
	v_pk_mul_f32 v[48:49], v[48:49], v[48:49]
	v_addc_co_u32_e32 v47, vcc, 0, v147, vcc
	v_cvt_pk_bf16_f32 v43, v48, v49
	v_max_f32_e32 v35, 0, v35
	v_max_f32_e32 v34, 0, v34
	v_max_f32_e32 v37, 0, v37
	v_max_f32_e32 v36, 0, v36
	v_cvt_pk_bf16_f32 v44, v44, v45
	v_cvt_pk_bf16_f32 v45, v52, v53
	global_store_dwordx4 v[46:47], v[42:45], off
	s_nop 1
	v_max_f32_e32 v39, 0, v39
	v_max_f32_e32 v38, 0, v38
	v_max_f32_e32 v41, 0, v41
	v_max_f32_e32 v40, 0, v40
	v_pk_mul_f32 v[42:43], v[36:37], v[36:37]
	v_pk_mul_f32 v[36:37], v[34:35], v[34:35]
	v_max_f32_e32 v31, 0, v31
	v_max_f32_e32 v30, 0, v30
	v_lshl_add_u64 v[50:51], v[146:147], 0, s[40:41]
	v_pk_mul_f32 v[40:41], v[40:41], v[40:41]
	v_pk_mul_f32 v[38:39], v[38:39], v[38:39]
	v_cvt_pk_bf16_f32 v34, v38, v39
	v_cvt_pk_bf16_f32 v35, v40, v41
	v_cvt_pk_bf16_f32 v36, v36, v37
	v_cvt_pk_bf16_f32 v37, v42, v43
	v_max_f32_e32 v27, 0, v27
	v_max_f32_e32 v26, 0, v26
	v_max_f32_e32 v29, 0, v29
	v_max_f32_e32 v28, 0, v28
	v_pk_mul_f32 v[30:31], v[30:31], v[30:31]
	global_store_dwordx4 v[50:51], v[34:37], off offset:256
	s_nop 1
	v_max_f32_e32 v33, 0, v33
	v_max_f32_e32 v32, 0, v32
	v_pk_mul_f32 v[36:37], v[28:29], v[28:29]
	v_pk_mul_f32 v[28:29], v[26:27], v[26:27]
	v_cvt_pk_bf16_f32 v26, v30, v31
	v_add_co_u32_e32 v30, vcc, s92, v146
	v_pk_mul_f32 v[32:33], v[32:33], v[32:33]
	v_addc_co_u32_e32 v31, vcc, 0, v147, vcc
	v_cvt_pk_bf16_f32 v27, v32, v33
	v_max_f32_e32 v19, 0, v19
	v_max_f32_e32 v18, 0, v18
	v_max_f32_e32 v21, 0, v21
	v_max_f32_e32 v20, 0, v20
	v_cvt_pk_bf16_f32 v28, v28, v29
	v_cvt_pk_bf16_f32 v29, v36, v37
	global_store_dwordx4 v[30:31], v[26:29], off
	s_nop 1
	v_max_f32_e32 v23, 0, v23
	v_max_f32_e32 v22, 0, v22
	v_max_f32_e32 v25, 0, v25
	v_max_f32_e32 v24, 0, v24
	v_pk_mul_f32 v[26:27], v[20:21], v[20:21]
	v_pk_mul_f32 v[20:21], v[18:19], v[18:19]
	v_max_f32_e32 v15, 0, v15
	v_max_f32_e32 v14, 0, v14
	v_lshl_add_u64 v[34:35], v[146:147], 0, s[42:43]
	v_pk_mul_f32 v[24:25], v[24:25], v[24:25]
	v_pk_mul_f32 v[22:23], v[22:23], v[22:23]
	v_cvt_pk_bf16_f32 v18, v22, v23
	v_cvt_pk_bf16_f32 v19, v24, v25
	v_cvt_pk_bf16_f32 v20, v20, v21
	v_cvt_pk_bf16_f32 v21, v26, v27
	v_max_f32_e32 v11, 0, v11
	v_max_f32_e32 v10, 0, v10
	v_max_f32_e32 v13, 0, v13
	v_max_f32_e32 v12, 0, v12
	v_pk_mul_f32 v[14:15], v[14:15], v[14:15]
	global_store_dwordx4 v[34:35], v[18:21], off offset:256
	s_nop 1
	v_max_f32_e32 v17, 0, v17
	v_max_f32_e32 v16, 0, v16
	v_pk_mul_f32 v[20:21], v[12:13], v[12:13]
	v_pk_mul_f32 v[12:13], v[10:11], v[10:11]
	v_cvt_pk_bf16_f32 v10, v14, v15
	v_add_co_u32_e32 v14, vcc, s93, v146
	v_pk_mul_f32 v[16:17], v[16:17], v[16:17]
	v_addc_co_u32_e32 v15, vcc, 0, v147, vcc
	v_cvt_pk_bf16_f32 v11, v16, v17
	v_max_f32_e32 v3, 0, v3
	v_max_f32_e32 v2, 0, v2
	v_max_f32_e32 v5, 0, v5
	v_max_f32_e32 v4, 0, v4
	v_lshl_add_u64 v[18:19], v[146:147], 0, s[44:45]
	v_cvt_pk_bf16_f32 v12, v12, v13
	v_cvt_pk_bf16_f32 v13, v20, v21
	global_store_dwordx4 v[14:15], v[10:13], off
	s_nop 1
	v_max_f32_e32 v7, 0, v7
	v_max_f32_e32 v6, 0, v6
	v_max_f32_e32 v9, 0, v9
	v_max_f32_e32 v8, 0, v8
	v_pk_mul_f32 v[10:11], v[4:5], v[4:5]
	v_pk_mul_f32 v[4:5], v[2:3], v[2:3]
	s_and_b64 vcc, exec, s[2:3]
	s_mov_b64 s[0:1], -1
	v_pk_mul_f32 v[8:9], v[8:9], v[8:9]
	v_pk_mul_f32 v[6:7], v[6:7], v[6:7]
	s_nop 0
	v_cvt_pk_bf16_f32 v2, v6, v7
	v_cvt_pk_bf16_f32 v3, v8, v9
	v_cvt_pk_bf16_f32 v4, v4, v5
	v_cvt_pk_bf16_f32 v5, v10, v11
	global_store_dwordx4 v[18:19], v[2:5], off offset:256
	s_cbranch_vccnz .LBB0_372
	s_andn2_b64 vcc, exec, s[6:7]
	s_cbranch_vccnz .LBB0_371
	s_barrier
	s_branch .LBB0_371

; __device__ __forceinline__ unsigned cvt_pk_bf16(float lo, float hi) { unsigned r; asm volatile("v_cvt_pk_bf16_f32 %0, %1, %2" : "=v"(r) : "v"(lo), "v"(hi)); return r; }
;     __device__ __forceinline__ void operator()(const f32x4 (&acc)[2][2][4][2], const Unit& u, int wr, int wc, int fr, int fq) const {
;     ...
;             for (int m = 0; m < 4; ++m) { bf16_t* rowp = O + (size_t)(row0 + ai * HALF + m * 16) * ldc + col0;
; #pragma unroll
;                 for (int bj = 0; bj < 2; ++bj) { f32x4 v0 = acc[ai][bj][m][0], v1 = acc[ai][bj][m][1];
;                     if (ACT == 1) { v0 = __builtin_elementwise_max(v0, (f32x4){0.f, 0.f, 0.f, 0.f}); v1 = __builtin_elementwise_max(v1, (f32x4){0.f, 0.f, 0.f, 0.f}); v0 = v0 * v0; v1 = v1 * v1; }
;                     if (ACT == 2) { v0 = v0 * sv[bj][0]; v1 = v1 * sv[bj][1]; }
;                     u32x4 w; w.x = cvt_pk_bf16(v0[0], v0[1]); w.y = cvt_pk_bf16(v0[2], v0[3]); w.z = cvt_pk_bf16(v1[0], v1[1]); w.w = cvt_pk_bf16(v1[2], v1[3]);
;                     *(u32x4*)(rowp + bj * HALF) = w; } }
.LBB0_1043:
	v_lshl_add_u32 v148, s40, 8, v1
	v_lshl_or_b32 v146, s73, 8, v153
	v_ashrrev_i32_e32 v149, 31, v148
	v_ashrrev_i32_e32 v147, 31, v146
	v_lshlrev_b64 v[150:151], 13, v[148:149]
	v_lshl_add_u64 v[158:159], s[20:21], 0, v[150:151]
	v_lshlrev_b64 v[150:151], 1, v[146:147]
	v_max_f32_e32 v127, 0, v127
	v_max_f32_e32 v126, 0, v126
	v_max_f32_e32 v129, 0, v129
	v_max_f32_e32 v128, 0, v128
	v_max_f32_e32 v123, 0, v123
	v_max_f32_e32 v122, 0, v122
	v_max_f32_e32 v125, 0, v125
	v_max_f32_e32 v124, 0, v124
	v_lshl_add_u64 v[146:147], v[158:159], 0, v[150:151]
	v_pk_mul_f32 v[128:129], v[128:129], v[128:129]
	v_pk_mul_f32 v[126:127], v[126:127], v[126:127]
	v_pk_mul_f32 v[158:159], v[124:125], v[124:125]
	v_pk_mul_f32 v[124:125], v[122:123], v[122:123]
	v_cvt_pk_bf16_f32 v122, v126, v127
	v_cvt_pk_bf16_f32 v123, v128, v129
	v_max_f32_e32 v119, 0, v119
	v_max_f32_e32 v118, 0, v118
	v_max_f32_e32 v115, 0, v115
	v_max_f32_e32 v114, 0, v114
	v_max_f32_e32 v117, 0, v117
	v_max_f32_e32 v116, 0, v116
	v_cvt_pk_bf16_f32 v124, v124, v125
	v_cvt_pk_bf16_f32 v125, v158, v159
	global_store_dwordx4 v[146:147], v[122:125], off
	s_nop 1
	v_max_f32_e32 v121, 0, v121
	v_max_f32_e32 v120, 0, v120
	v_pk_mul_f32 v[118:119], v[118:119], v[118:119]
	v_pk_mul_f32 v[122:123], v[116:117], v[116:117]
	v_pk_mul_f32 v[116:117], v[114:115], v[114:115]
	v_cvt_pk_bf16_f32 v114, v118, v119
	v_pk_mul_f32 v[120:121], v[120:121], v[120:121]
	v_cvt_pk_bf16_f32 v115, v120, v121
	v_cvt_pk_bf16_f32 v116, v116, v117
	v_cvt_pk_bf16_f32 v117, v122, v123
	global_store_dwordx4 v[146:147], v[114:117], off offset:256
	s_nop 1
	v_or_b32_e32 v114, 16, v148
	v_ashrrev_i32_e32 v115, 31, v114
	v_lshlrev_b64 v[114:115], 13, v[114:115]
	v_lshl_add_u64 v[114:115], s[20:21], 0, v[114:115]
	v_max_f32_e32 v111, 0, v111
	v_max_f32_e32 v110, 0, v110
	v_max_f32_e32 v113, 0, v113
	v_max_f32_e32 v112, 0, v112
	v_max_f32_e32 v107, 0, v107
	v_max_f32_e32 v106, 0, v106
	v_max_f32_e32 v109, 0, v109
	v_max_f32_e32 v108, 0, v108
	v_lshl_add_u64 v[114:115], v[114:115], 0, v[150:151]
	v_pk_mul_f32 v[112:113], v[112:113], v[112:113]
	v_pk_mul_f32 v[110:111], v[110:111], v[110:111]
	v_pk_mul_f32 v[116:117], v[108:109], v[108:109]
	v_pk_mul_f32 v[108:109], v[106:107], v[106:107]
	v_cvt_pk_bf16_f32 v106, v110, v111
	v_cvt_pk_bf16_f32 v107, v112, v113
	v_max_f32_e32 v103, 0, v103
	v_max_f32_e32 v102, 0, v102
	v_max_f32_e32 v99, 0, v99
	v_max_f32_e32 v98, 0, v98
	v_max_f32_e32 v101, 0, v101
	v_max_f32_e32 v100, 0, v100
	v_cvt_pk_bf16_f32 v108, v108, v109
	v_cvt_pk_bf16_f32 v109, v116, v117
	global_store_dwordx4 v[114:115], v[106:109], off
	s_nop 1
	v_max_f32_e32 v105, 0, v105
	v_max_f32_e32 v104, 0, v104
	v_pk_mul_f32 v[102:103], v[102:103], v[102:103]
	v_pk_mul_f32 v[106:107], v[100:101], v[100:101]
	v_pk_mul_f32 v[100:101], v[98:99], v[98:99]
	v_cvt_pk_bf16_f32 v98, v102, v103
	v_pk_mul_f32 v[104:105], v[104:105], v[104:105]
	v_cvt_pk_bf16_f32 v99, v104, v105
	v_cvt_pk_bf16_f32 v100, v100, v101
	v_cvt_pk_bf16_f32 v101, v106, v107
	global_store_dwordx4 v[114:115], v[98:101], off offset:256
	s_nop 1
	v_or_b32_e32 v98, 32, v148
	v_ashrrev_i32_e32 v99, 31, v98
	v_lshlrev_b64 v[98:99], 13, v[98:99]
	v_lshl_add_u64 v[98:99], s[20:21], 0, v[98:99]
	v_max_f32_e32 v95, 0, v95
	v_max_f32_e32 v94, 0, v94
	v_max_f32_e32 v97, 0, v97
	v_max_f32_e32 v96, 0, v96
	v_max_f32_e32 v91, 0, v91
	v_max_f32_e32 v90, 0, v90
	v_max_f32_e32 v93, 0, v93
	v_max_f32_e32 v92, 0, v92
	v_lshl_add_u64 v[98:99], v[98:99], 0, v[150:151]
	v_pk_mul_f32 v[96:97], v[96:97], v[96:97]
	v_pk_mul_f32 v[94:95], v[94:95], v[94:95]
	v_pk_mul_f32 v[100:101], v[92:93], v[92:93]
	v_pk_mul_f32 v[92:93], v[90:91], v[90:91]
	v_cvt_pk_bf16_f32 v90, v94, v95
	v_cvt_pk_bf16_f32 v91, v96, v97
	v_max_f32_e32 v87, 0, v87
	v_max_f32_e32 v86, 0, v86
	v_max_f32_e32 v83, 0, v83
	v_max_f32_e32 v82, 0, v82
	v_max_f32_e32 v85, 0, v85
	v_max_f32_e32 v84, 0, v84
	v_cvt_pk_bf16_f32 v92, v92, v93
	v_cvt_pk_bf16_f32 v93, v100, v101
	global_store_dwordx4 v[98:99], v[90:93], off
	s_nop 1
	v_max_f32_e32 v89, 0, v89
	v_max_f32_e32 v88, 0, v88
	v_pk_mul_f32 v[86:87], v[86:87], v[86:87]
	v_pk_mul_f32 v[90:91], v[84:85], v[84:85]
	v_pk_mul_f32 v[84:85], v[82:83], v[82:83]
	v_cvt_pk_bf16_f32 v82, v86, v87
	v_pk_mul_f32 v[88:89], v[88:89], v[88:89]
	v_cvt_pk_bf16_f32 v83, v88, v89
	v_cvt_pk_bf16_f32 v84, v84, v85
	v_cvt_pk_bf16_f32 v85, v90, v91
	global_store_dwordx4 v[98:99], v[82:85], off offset:256
	s_nop 1
	v_or_b32_e32 v82, 48, v148
	v_ashrrev_i32_e32 v83, 31, v82
	v_lshlrev_b64 v[82:83], 13, v[82:83]
	v_lshl_add_u64 v[82:83], s[20:21], 0, v[82:83]
	v_max_f32_e32 v79, 0, v79
	v_max_f32_e32 v78, 0, v78
	v_max_f32_e32 v81, 0, v81
	v_max_f32_e32 v80, 0, v80
	v_max_f32_e32 v75, 0, v75
	v_max_f32_e32 v74, 0, v74
	v_max_f32_e32 v77, 0, v77
	v_max_f32_e32 v76, 0, v76
	v_lshl_add_u64 v[82:83], v[82:83], 0, v[150:151]
	v_pk_mul_f32 v[80:81], v[80:81], v[80:81]
	v_pk_mul_f32 v[78:79], v[78:79], v[78:79]
	v_pk_mul_f32 v[84:85], v[76:77], v[76:77]
	v_pk_mul_f32 v[76:77], v[74:75], v[74:75]
	v_cvt_pk_bf16_f32 v74, v78, v79
	v_cvt_pk_bf16_f32 v75, v80, v81
	v_max_f32_e32 v67, 0, v67
	v_max_f32_e32 v66, 0, v66
	v_max_f32_e32 v69, 0, v69
	v_max_f32_e32 v68, 0, v68
	v_cvt_pk_bf16_f32 v76, v76, v77
	v_cvt_pk_bf16_f32 v77, v84, v85
	global_store_dwordx4 v[82:83], v[74:77], off
	s_nop 1
	v_max_f32_e32 v71, 0, v71
	v_max_f32_e32 v70, 0, v70
	v_max_f32_e32 v73, 0, v73
	v_max_f32_e32 v72, 0, v72
	v_pk_mul_f32 v[74:75], v[68:69], v[68:69]
	v_pk_mul_f32 v[68:69], v[66:67], v[66:67]
	v_max_f32_e32 v63, 0, v63
; __device__ __forceinline__ unsigned cvt_pk_bf16(float lo, float hi) { unsigned r; asm volatile("v_cvt_pk_bf16_f32 %0, %1, %2" : "=v"(r) : "v"(lo), "v"(hi)); return r; }
;     __device__ __forceinline__ void operator()(const f32x4 (&acc)[2][2][4][2], const Unit& u, int wr, int wc, int fr, int fq) const {
;     ...
;             for (int m = 0; m < 4; ++m) { bf16_t* rowp = O + (size_t)(row0 + ai * HALF + m * 16) * ldc + col0;
; #pragma unroll
;                 for (int bj = 0; bj < 2; ++bj) { f32x4 v0 = acc[ai][bj][m][0], v1 = acc[ai][bj][m][1];
;                     if (ACT == 1) { v0 = __builtin_elementwise_max(v0, (f32x4){0.f, 0.f, 0.f, 0.f}); v1 = __builtin_elementwise_max(v1, (f32x4){0.f, 0.f, 0.f, 0.f}); v0 = v0 * v0; v1 = v1 * v1; }
;                     if (ACT == 2) { v0 = v0 * sv[bj][0]; v1 = v1 * sv[bj][1]; }
;                     u32x4 w; w.x = cvt_pk_bf16(v0[0], v0[1]); w.y = cvt_pk_bf16(v0[2], v0[3]); w.z = cvt_pk_bf16(v1[0], v1[1]); w.w = cvt_pk_bf16(v1[2], v1[3]);
;                     *(u32x4*)(rowp + bj * HALF) = w; } }
	v_max_f32_e32 v62, 0, v62
	v_pk_mul_f32 v[72:73], v[72:73], v[72:73]
	v_pk_mul_f32 v[70:71], v[70:71], v[70:71]
	v_cvt_pk_bf16_f32 v66, v70, v71
	v_cvt_pk_bf16_f32 v67, v72, v73
	v_cvt_pk_bf16_f32 v68, v68, v69
	v_cvt_pk_bf16_f32 v69, v74, v75
	v_max_f32_e32 v59, 0, v59
	v_max_f32_e32 v58, 0, v58
	v_max_f32_e32 v61, 0, v61
	v_max_f32_e32 v60, 0, v60
	v_pk_mul_f32 v[62:63], v[62:63], v[62:63]
	global_store_dwordx4 v[82:83], v[66:69], off offset:256
	s_nop 1
	v_max_f32_e32 v65, 0, v65
	v_max_f32_e32 v64, 0, v64
	v_pk_mul_f32 v[68:69], v[60:61], v[60:61]
	v_pk_mul_f32 v[60:61], v[58:59], v[58:59]
	v_cvt_pk_bf16_f32 v58, v62, v63
	v_add_co_u32_e32 v62, vcc, s68, v146
	v_pk_mul_f32 v[64:65], v[64:65], v[64:65]
	v_addc_co_u32_e32 v63, vcc, 0, v147, vcc
	v_cvt_pk_bf16_f32 v59, v64, v65
	v_max_f32_e32 v51, 0, v51
	v_max_f32_e32 v50, 0, v50
	v_max_f32_e32 v53, 0, v53
	v_max_f32_e32 v52, 0, v52
	v_cvt_pk_bf16_f32 v60, v60, v61
	v_cvt_pk_bf16_f32 v61, v68, v69
	global_store_dwordx4 v[62:63], v[58:61], off
	s_nop 1
	v_max_f32_e32 v55, 0, v55
	v_max_f32_e32 v54, 0, v54
	v_max_f32_e32 v57, 0, v57
	v_max_f32_e32 v56, 0, v56
	v_pk_mul_f32 v[58:59], v[52:53], v[52:53]
	v_pk_mul_f32 v[52:53], v[50:51], v[50:51]
	v_max_f32_e32 v47, 0, v47
	v_max_f32_e32 v46, 0, v46
	v_lshl_add_u64 v[66:67], v[146:147], 0, s[16:17]
	v_pk_mul_f32 v[56:57], v[56:57], v[56:57]
	v_pk_mul_f32 v[54:55], v[54:55], v[54:55]
	v_cvt_pk_bf16_f32 v50, v54, v55
	v_cvt_pk_bf16_f32 v51, v56, v57
	v_cvt_pk_bf16_f32 v52, v52, v53
	v_cvt_pk_bf16_f32 v53, v58, v59
	v_max_f32_e32 v43, 0, v43
	v_max_f32_e32 v42, 0, v42
	v_max_f32_e32 v45, 0, v45
	v_max_f32_e32 v44, 0, v44
	v_pk_mul_f32 v[46:47], v[46:47], v[46:47]
	global_store_dwordx4 v[66:67], v[50:53], off offset:256
	s_nop 1
	v_max_f32_e32 v49, 0, v49
	v_max_f32_e32 v48, 0, v48
	v_pk_mul_f32 v[52:53], v[44:45], v[44:45]
	v_pk_mul_f32 v[44:45], v[42:43], v[42:43]
	v_cvt_pk_bf16_f32 v42, v46, v47
	v_add_co_u32_e32 v46, vcc, s69, v146
	v_pk_mul_f32 v[48:49], v[48:49], v[48:49]
	v_addc_co_u32_e32 v47, vcc, 0, v147, vcc
	v_cvt_pk_bf16_f32 v43, v48, v49
	v_max_f32_e32 v35, 0, v35
	v_max_f32_e32 v34, 0, v34
	v_max_f32_e32 v37, 0, v37
	v_max_f32_e32 v36, 0, v36
	v_cvt_pk_bf16_f32 v44, v44, v45
	v_cvt_pk_bf16_f32 v45, v52, v53
	global_store_dwordx4 v[46:47], v[42:45], off
	s_nop 1
	v_max_f32_e32 v39, 0, v39
	v_max_f32_e32 v38, 0, v38
	v_max_f32_e32 v41, 0, v41
	v_max_f32_e32 v40, 0, v40
	v_pk_mul_f32 v[42:43], v[36:37], v[36:37]
	v_pk_mul_f32 v[36:37], v[34:35], v[34:35]
	v_max_f32_e32 v31, 0, v31
	v_max_f32_e32 v30, 0, v30
	v_lshl_add_u64 v[50:51], v[146:147], 0, s[24:25]
	v_pk_mul_f32 v[40:41], v[40:41], v[40:41]
	v_pk_mul_f32 v[38:39], v[38:39], v[38:39]
	v_cvt_pk_bf16_f32 v34, v38, v39
	v_cvt_pk_bf16_f32 v35, v40, v41
	v_cvt_pk_bf16_f32 v36, v36, v37
	v_cvt_pk_bf16_f32 v37, v42, v43
	v_max_f32_e32 v27, 0, v27
	v_max_f32_e32 v26, 0, v26
	v_max_f32_e32 v29, 0, v29
	v_max_f32_e32 v28, 0, v28
	v_pk_mul_f32 v[30:31], v[30:31], v[30:31]
	global_store_dwordx4 v[50:51], v[34:37], off offset:256
	s_nop 1
	v_max_f32_e32 v33, 0, v33
	v_max_f32_e32 v32, 0, v32
	v_pk_mul_f32 v[36:37], v[28:29], v[28:29]
	v_pk_mul_f32 v[28:29], v[26:27], v[26:27]
	v_cvt_pk_bf16_f32 v26, v30, v31
	v_add_co_u32_e32 v30, vcc, s70, v146
	v_pk_mul_f32 v[32:33], v[32:33], v[32:33]
	v_addc_co_u32_e32 v31, vcc, 0, v147, vcc
	v_cvt_pk_bf16_f32 v27, v32, v33
	v_max_f32_e32 v19, 0, v19
	v_max_f32_e32 v18, 0, v18
	v_max_f32_e32 v21, 0, v21
	v_max_f32_e32 v20, 0, v20
	v_cvt_pk_bf16_f32 v28, v28, v29
	v_cvt_pk_bf16_f32 v29, v36, v37
	global_store_dwordx4 v[30:31], v[26:29], off
	s_nop 1
	v_max_f32_e32 v23, 0, v23
	v_max_f32_e32 v22, 0, v22
	v_max_f32_e32 v25, 0, v25
	v_max_f32_e32 v24, 0, v24
	v_pk_mul_f32 v[26:27], v[20:21], v[20:21]
	v_pk_mul_f32 v[20:21], v[18:19], v[18:19]
	v_max_f32_e32 v15, 0, v15
	v_max_f32_e32 v14, 0, v14
	v_lshl_add_u64 v[34:35], v[146:147], 0, s[26:27]
	v_pk_mul_f32 v[24:25], v[24:25], v[24:25]
	v_pk_mul_f32 v[22:23], v[22:23], v[22:23]
	v_cvt_pk_bf16_f32 v18, v22, v23
	v_cvt_pk_bf16_f32 v19, v24, v25
	v_cvt_pk_bf16_f32 v20, v20, v21
	v_cvt_pk_bf16_f32 v21, v26, v27
	v_max_f32_e32 v11, 0, v11
	v_max_f32_e32 v10, 0, v10
	v_max_f32_e32 v13, 0, v13
	v_max_f32_e32 v12, 0, v12
	v_pk_mul_f32 v[14:15], v[14:15], v[14:15]
	global_store_dwordx4 v[34:35], v[18:21], off offset:256
	s_nop 1
	v_max_f32_e32 v17, 0, v17
	v_max_f32_e32 v16, 0, v16
	v_pk_mul_f32 v[20:21], v[12:13], v[12:13]
	v_pk_mul_f32 v[12:13], v[10:11], v[10:11]
	v_cvt_pk_bf16_f32 v10, v14, v15
	v_add_co_u32_e32 v14, vcc, s71, v146
	v_pk_mul_f32 v[16:17], v[16:17], v[16:17]
	v_addc_co_u32_e32 v15, vcc, 0, v147, vcc
	v_cvt_pk_bf16_f32 v11, v16, v17
	v_max_f32_e32 v3, 0, v3
	v_max_f32_e32 v2, 0, v2
	v_max_f32_e32 v5, 0, v5
	v_max_f32_e32 v4, 0, v4
	v_lshl_add_u64 v[18:19], v[146:147], 0, s[28:29]
	v_cvt_pk_bf16_f32 v12, v12, v13
	v_cvt_pk_bf16_f32 v13, v20, v21
	global_store_dwordx4 v[14:15], v[10:13], off
	s_nop 1
	v_max_f32_e32 v7, 0, v7
	v_max_f32_e32 v6, 0, v6
	v_max_f32_e32 v9, 0, v9
	v_max_f32_e32 v8, 0, v8
	v_pk_mul_f32 v[10:11], v[4:5], v[4:5]
	v_pk_mul_f32 v[4:5], v[2:3], v[2:3]
	s_and_b64 vcc, exec, s[2:3]
	s_mov_b64 s[0:1], -1
	v_pk_mul_f32 v[8:9], v[8:9], v[8:9]
	v_pk_mul_f32 v[6:7], v[6:7], v[6:7]
	s_nop 0
	v_cvt_pk_bf16_f32 v2, v6, v7
	v_cvt_pk_bf16_f32 v3, v8, v9
	v_cvt_pk_bf16_f32 v4, v4, v5
	v_cvt_pk_bf16_f32 v5, v10, v11
	global_store_dwordx4 v[18:19], v[2:5], off offset:256
	s_nop 1
	s_cbranch_vccnz .LBB0_1030
	s_andn2_b64 vcc, exec, s[6:7]
	s_cbranch_vccnz .LBB0_1029
	s_barrier
	s_branch .LBB0_1029
